# plus: sample-row norm steps (P7/P10) issue their tail gain/residual loads with the first batch (no load-wait ladders behind write-through stores)
# baseline (speedup 1.0000x reference)
.LBB0_832:
	v_lshl_add_u64 v[18:19], s[12:13], 0, v[12:13]
	v_add_co_u32_e32 v58, vcc, s14, v18
	v_lshl_add_u64 v[20:21], s[12:13], 0, v[16:17]
	s_nop 0
	v_addc_co_u32_e32 v59, vcc, 0, v19, vcc
	v_add_co_u32_e32 v62, vcc, s15, v18
	v_lshl_add_u64 v[34:35], s[12:13], 0, v[14:15]
	s_nop 0
	v_addc_co_u32_e32 v63, vcc, 0, v19, vcc
	s_waitcnt vmcnt(14)
	v_add_co_u32_e32 v78, vcc, s24, v18
	global_load_dwordx4 v[0:3], v[8:9], off
	global_load_dwordx4 v[4:7], v[8:9], off offset:1024
	global_load_dwordx4 v[26:29], v[8:9], off offset:2048
	global_load_dwordx4 v[30:33], v[8:9], off offset:3072
	v_addc_co_u32_e32 v79, vcc, 0, v19, vcc
	s_waitcnt vmcnt(14)
	v_add_co_u32_e32 v94, vcc, s25, v18
	s_add_i32 s8, s40, 0x4000
	s_nop 0
	v_addc_co_u32_e32 v95, vcc, 0, v19, vcc
	v_add_co_u32_e32 v20, vcc, s27, v20
	s_cmpk_lt_i32 s8, 0x4000
	s_nop 0
	v_addc_co_u32_e32 v21, vcc, 0, v21, vcc
	v_add_co_u32_e32 v18, vcc, s30, v34
	s_cselect_b32 s9, s43, 0
	s_nop 0
	v_addc_co_u32_e32 v19, vcc, 0, v35, vcc
	global_load_dwordx4 v[34:37], v[62:63], off
	global_load_dwordx4 v[38:41], v[58:59], off
	global_load_dwordx4 v[42:45], v[58:59], off offset:1024
	global_load_dwordx4 v[46:49], v[62:63], off offset:1024
	global_load_dwordx4 v[50:53], v[62:63], off offset:2048
	global_load_dwordx4 v[54:57], v[58:59], off offset:2048
	s_nop 0
	global_load_dwordx4 v[58:61], v[58:59], off offset:3072
	s_nop 0
	global_load_dwordx4 v[62:65], v[62:63], off offset:3072
	s_nop 0
	global_load_dwordx4 v[66:69], v[78:79], off
	global_load_dwordx4 v[70:73], v[78:79], off offset:1024
	global_load_dwordx4 v[74:77], v[78:79], off offset:2048
	s_nop 0
	global_load_dwordx4 v[78:81], v[78:79], off offset:3072
	s_nop 0
	global_load_dwordx4 v[82:85], v[94:95], off
	global_load_dwordx4 v[86:89], v[94:95], off offset:1024
	global_load_dwordx4 v[90:93], v[94:95], off offset:2048
	s_nop 0
	global_load_dwordx4 v[94:97], v[94:95], off offset:3072
	s_cselect_b32 s8, s42, s40
	s_cselect_b32 s31, s17, s19
	s_cselect_b32 s41, s16, s18
	s_lshl_b64 s[8:9], s[8:9], 12
	s_add_u32 s8, s41, s8
	s_addc_u32 s9, s31, s9
	global_load_dwordx4 v[98:101], v22, s[8:9]
	global_load_dwordx4 v[102:105], v22, s[8:9] offset:1024
	global_load_dwordx4 v[106:109], v22, s[8:9] offset:2048
	global_load_dwordx4 v[110:113], v22, s[8:9] offset:3072
	global_load_dwordx4 v[114:117], v[10:11], off
	global_load_dwordx4 v[118:121], v[10:11], off offset:1024
	global_load_dwordx4 v[122:125], v[10:11], off offset:2048
	global_load_dwordx4 v[126:129], v[10:11], off offset:3072
	s_add_i32 s40, s40, s34
	v_lshl_add_u64 v[12:13], v[12:13], 0, s[44:45]
	v_lshl_add_u64 v[14:15], v[14:15], 0, s[46:47]
	v_lshl_add_u64 v[16:17], v[16:17], 0, s[44:45]
	s_waitcnt vmcnt(22)
	v_pk_add_f32 v[36:37], v[40:41], v[36:37]
	v_pk_add_f32 v[34:35], v[38:39], v[34:35]
	s_waitcnt vmcnt(20)
	v_pk_add_f32 v[38:39], v[44:45], v[48:49]
	v_pk_add_f32 v[40:41], v[42:43], v[46:47]
	s_waitcnt vmcnt(18)
	v_pk_add_f32 v[42:43], v[56:57], v[52:53]
	v_pk_add_f32 v[44:45], v[54:55], v[50:51]
	s_waitcnt vmcnt(16)
	v_pk_add_f32 v[46:47], v[60:61], v[64:65]
	s_waitcnt vmcnt(15)
	v_pk_add_f32 v[36:37], v[36:37], v[68:69]
	v_pk_add_f32 v[34:35], v[34:35], v[66:67]
	s_waitcnt vmcnt(14)
	v_pk_add_f32 v[38:39], v[38:39], v[72:73]
	v_pk_add_f32 v[40:41], v[40:41], v[70:71]
	v_pk_add_f32 v[48:49], v[58:59], v[62:63]
	s_waitcnt vmcnt(13)
	v_pk_add_f32 v[42:43], v[42:43], v[76:77]
	v_pk_add_f32 v[44:45], v[44:45], v[74:75]
	s_waitcnt vmcnt(11)
	v_pk_add_f32 v[36:37], v[36:37], v[84:85]
	v_pk_add_f32 v[34:35], v[34:35], v[82:83]
	s_waitcnt vmcnt(10)
	v_pk_add_f32 v[38:39], v[38:39], v[88:89]
	v_pk_add_f32 v[40:41], v[40:41], v[86:87]
	v_pk_add_f32 v[46:47], v[46:47], v[80:81]
	v_pk_add_f32 v[48:49], v[48:49], v[78:79]
	s_waitcnt vmcnt(9)
	v_pk_add_f32 v[42:43], v[42:43], v[92:93]
	v_pk_add_f32 v[44:45], v[44:45], v[90:91]
	v_mul_f32_e32 v25, v35, v35
	v_mul_f32_e32 v50, v37, v37
	v_mul_f32_e32 v51, v41, v41
	v_mul_f32_e32 v52, v39, v39
	s_waitcnt vmcnt(8)
	v_pk_add_f32 v[46:47], v[46:47], v[96:97]
	v_pk_add_f32 v[48:49], v[48:49], v[94:95]
	v_mul_f32_e32 v53, v45, v45
	v_mul_f32_e32 v54, v43, v43
	v_fmac_f32_e32 v25, v34, v34
	v_fmac_f32_e32 v50, v36, v36
	v_fmac_f32_e32 v51, v40, v40
	v_fmac_f32_e32 v52, v38, v38
	v_mul_f32_e32 v55, v49, v49
	v_mul_f32_e32 v56, v47, v47
	v_fmac_f32_e32 v53, v44, v44
	v_fmac_f32_e32 v54, v42, v42
	v_add_f32_e32 v25, v25, v50
	v_add_f32_e32 v50, v51, v52
	v_fmac_f32_e32 v55, v48, v48
	v_fmac_f32_e32 v56, v46, v46
	v_add_f32_e32 v51, v53, v54
	v_add_f32_e32 v25, v25, v50
	v_add_f32_e32 v52, v55, v56
	v_add_f32_e32 v25, v25, v51
	v_add_f32_e32 v25, v25, v52
	s_nop 1
	v_add_f32_dpp v25, v25, v25 quad_perm:[1,0,3,2] row_mask:0xf bank_mask:0xf bound_ctrl:1
	s_nop 1
	v_add_f32_dpp v25, v25, v25 quad_perm:[2,3,0,1] row_mask:0xf bank_mask:0xf bound_ctrl:1
	s_nop 1
	v_add_f32_dpp v25, v25, v25 row_half_mirror row_mask:0xf bank_mask:0xf bound_ctrl:1
	s_nop 1
	v_add_f32_dpp v25, v25, v25 row_ror:8 row_mask:0xf bank_mask:0xf bound_ctrl:1
	v_mov_b32_e32 v50, v25
	s_nop 1
	v_permlane16_swap_b32_e32 v25, v50
	v_add_f32_e32 v25, v25, v50
	v_mov_b32_e32 v50, v25
	s_nop 1
	v_permlane32_swap_b32_e32 v25, v50
	v_add_f32_e32 v25, v25, v50
	v_fmamk_f32 v25, v25, 0x3a800000, v23
	v_mul_f32_e32 v50, 0x4f800000, v25
	v_cmp_gt_f32_e32 vcc, s26, v25
	s_nop 1
	v_cndmask_b32_e32 v25, v25, v50, vcc
	v_sqrt_f32_e32 v50, v25
	s_nop 0
	v_add_u32_e32 v51, -1, v50
	v_add_u32_e32 v52, 1, v50
	v_fma_f32 v53, -v51, v50, v25
	v_fma_f32 v54, -v52, v50, v25
	v_cmp_ge_f32_e64 s[8:9], 0, v53
	s_nop 1
	v_cndmask_b32_e64 v50, v50, v51, s[8:9]
	v_cmp_lt_f32_e64 s[8:9], 0, v54
	s_nop 1
	v_cndmask_b32_e64 v50, v50, v52, s[8:9]
	v_mul_f32_e32 v51, 0x37800000, v50
	v_cndmask_b32_e32 v50, v50, v51, vcc
	v_cmp_class_f32_e32 vcc, v25, v24
	s_nop 1
	v_cndmask_b32_e32 v25, v50, v25, vcc
	v_div_scale_f32 v50, s[8:9], v25, v25, 1.0
	v_rcp_f32_e32 v52, v50
	v_div_scale_f32 v51, vcc, 1.0, v25, 1.0
	v_fma_f32 v53, -v50, v52, 1.0
	v_fmac_f32_e32 v52, v53, v52
	v_mul_f32_e32 v53, v51, v52
	v_fma_f32 v54, -v50, v53, v51
	v_fmac_f32_e32 v53, v54, v52
	v_fma_f32 v50, -v50, v53, v51
	v_div_fmas_f32 v50, v50, v52, v53
	v_div_fixup_f32 v50, v50, v25, 1.0
	v_pk_mul_f32 v[34:35], v[34:35], v[50:51] op_sel_hi:[1,0]
	v_pk_mul_f32 v[36:37], v[36:37], v[50:51] op_sel_hi:[1,0]
	s_waitcnt vmcnt(7)
	v_pk_fma_f32 v[0:1], v[0:1], v[34:35], v[98:99]
	v_pk_fma_f32 v[2:3], v[2:3], v[36:37], v[100:101]
	global_store_dwordx4 v[20:21], v[0:3], off sc1
	v_pk_mul_f32 v[40:41], v[40:41], v[50:51] op_sel_hi:[1,0]
	v_pk_mul_f32 v[38:39], v[38:39], v[50:51] op_sel_hi:[1,0]
	v_pk_mul_f32 v[44:45], v[44:45], v[50:51] op_sel_hi:[1,0]
	v_pk_mul_f32 v[42:43], v[42:43], v[50:51] op_sel_hi:[1,0]
	s_waitcnt vmcnt(7)
	v_pk_fma_f32 v[6:7], v[6:7], v[38:39], v[104:105]
	v_pk_fma_f32 v[4:5], v[4:5], v[40:41], v[102:103]
	v_pk_mul_f32 v[48:49], v[48:49], v[50:51] op_sel_hi:[1,0]
	v_pk_mul_f32 v[46:47], v[46:47], v[50:51] op_sel_hi:[1,0]
	s_waitcnt vmcnt(6)
	v_pk_fma_f32 v[28:29], v[28:29], v[42:43], v[108:109]
	v_pk_fma_f32 v[26:27], v[26:27], v[44:45], v[106:107]
	v_mul_f32_e32 v25, v1, v1
	v_mul_f32_e32 v38, v3, v3
	v_mul_f32_e32 v39, v5, v5
	v_mul_f32_e32 v40, v7, v7
	s_waitcnt vmcnt(5)
	v_pk_fma_f32 v[32:33], v[32:33], v[46:47], v[112:113]
	v_pk_fma_f32 v[30:31], v[30:31], v[48:49], v[110:111]
	v_mul_f32_e32 v41, v27, v27
	v_mul_f32_e32 v42, v29, v29
	v_fmac_f32_e32 v25, v0, v0
	v_fmac_f32_e32 v38, v2, v2
	v_fmac_f32_e32 v39, v4, v4
	v_fmac_f32_e32 v40, v6, v6
	v_mul_f32_e32 v43, v31, v31
	v_mul_f32_e32 v44, v33, v33
	v_fmac_f32_e32 v41, v26, v26
	v_fmac_f32_e32 v42, v28, v28
	v_add_f32_e32 v25, v25, v38
	v_add_f32_e32 v38, v39, v40
	v_fmac_f32_e32 v43, v30, v30
	v_fmac_f32_e32 v44, v32, v32
	v_add_f32_e32 v39, v41, v42
	v_add_f32_e32 v25, v25, v38
	v_add_f32_e32 v40, v43, v44
	v_add_f32_e32 v25, v39, v25
	v_add_f32_e32 v25, v40, v25
	s_nop 1
	v_add_f32_dpp v25, v25, v25 quad_perm:[1,0,3,2] row_mask:0xf bank_mask:0xf bound_ctrl:1
	s_nop 1
	v_add_f32_dpp v25, v25, v25 quad_perm:[2,3,0,1] row_mask:0xf bank_mask:0xf bound_ctrl:1
	s_nop 1
	v_add_f32_dpp v25, v25, v25 row_half_mirror row_mask:0xf bank_mask:0xf bound_ctrl:1
	s_nop 1
	v_add_f32_dpp v25, v25, v25 row_ror:8 row_mask:0xf bank_mask:0xf bound_ctrl:1
	v_mov_b32_e32 v38, v25
	s_nop 1
	v_permlane16_swap_b32_e32 v25, v38
	v_add_f32_e32 v25, v25, v38
	v_mov_b32_e32 v38, v25
	s_nop 1
	v_permlane32_swap_b32_e32 v25, v38
	v_add_f32_e32 v25, v25, v38
	v_fmamk_f32 v25, v25, 0x3a800000, v23
	v_mul_f32_e32 v38, 0x4f800000, v25
	v_cmp_gt_f32_e32 vcc, s26, v25
	s_nop 1
	v_cndmask_b32_e32 v25, v25, v38, vcc
	v_sqrt_f32_e32 v38, v25
	s_nop 0
	v_add_u32_e32 v39, -1, v38
	v_add_u32_e32 v40, 1, v38
	v_fma_f32 v41, -v39, v38, v25
	v_fma_f32 v42, -v40, v38, v25
	v_cmp_ge_f32_e64 s[8:9], 0, v41
	s_nop 1
	v_cndmask_b32_e64 v38, v38, v39, s[8:9]
	v_cmp_lt_f32_e64 s[8:9], 0, v42
	s_nop 1
	v_cndmask_b32_e64 v38, v38, v40, s[8:9]
	v_mul_f32_e32 v39, 0x37800000, v38
	v_cndmask_b32_e32 v38, v38, v39, vcc
	v_cmp_class_f32_e32 vcc, v25, v24
	s_nop 1
	v_cndmask_b32_e32 v25, v38, v25, vcc
	v_div_scale_f32 v38, s[8:9], v25, v25, 1.0
	v_rcp_f32_e32 v40, v38
	v_div_scale_f32 v39, vcc, 1.0, v25, 1.0
	s_add_i32 s8, s40, 0x4000
	v_fma_f32 v41, -v38, v40, 1.0
	v_fmac_f32_e32 v40, v41, v40
	v_mul_f32_e32 v41, v39, v40
	v_fma_f32 v42, -v38, v41, v39
	v_fmac_f32_e32 v41, v42, v40
	v_fma_f32 v38, -v38, v41, v39
	v_div_fmas_f32 v38, v38, v40, v41
	v_div_fixup_f32 v25, v38, v25, 1.0
	v_mul_f32_e32 v0, v0, v25
	v_mul_f32_e32 v2, v2, v25
	v_mul_f32_e32 v1, v1, v25
	v_mul_f32_e32 v3, v3, v25
	s_waitcnt vmcnt(4)
	v_mul_f32_e32 v0, v114, v0
	v_mul_f32_e32 v2, v116, v2
	v_mul_f32_e32 v1, v115, v1
	v_mul_f32_e32 v3, v117, v3
	v_bfe_u32 v34, v0, 16, 1
	v_bfe_u32 v36, v2, 16, 1
	v_bfe_u32 v35, v1, 16, 1
	v_bfe_u32 v37, v3, 16, 1
	v_add3_u32 v0, v0, v34, s28
	v_add3_u32 v2, v2, v36, s28
	v_add3_u32 v1, v1, v35, s28
	v_add3_u32 v3, v3, v37, s28
	v_lshrrev_b32_e32 v0, 16, v0
	v_lshrrev_b32_e32 v2, 16, v2
	v_and_or_b32 v0, v1, s29, v0
	v_and_or_b32 v1, v3, s29, v2
	global_store_dwordx2 v[18:19], v[0:1], off sc1
	global_store_dwordx4 v[20:21], v[4:7], off offset:1024 sc1
	s_add_u32 s42, s42, s34
	v_mul_f32_e32 v4, v4, v25
	v_mul_f32_e32 v6, v6, v25
	v_mul_f32_e32 v5, v5, v25
	v_mul_f32_e32 v7, v7, v25
	s_addc_u32 s43, s43, s35
	s_cmpk_gt_i32 s8, 0x407f
	s_waitcnt vmcnt(5)
	v_mul_f32_e32 v0, v118, v4
	v_mul_f32_e32 v2, v120, v6
	v_mul_f32_e32 v1, v119, v5
	v_mul_f32_e32 v3, v121, v7
	v_bfe_u32 v4, v0, 16, 1
	v_bfe_u32 v6, v2, 16, 1
	v_bfe_u32 v5, v1, 16, 1
	v_bfe_u32 v7, v3, 16, 1
	v_add3_u32 v0, v0, v4, s28
	v_add3_u32 v2, v2, v6, s28
	v_add3_u32 v1, v1, v5, s28
	v_add3_u32 v3, v3, v7, s28
	v_lshrrev_b32_e32 v0, 16, v0
	v_lshrrev_b32_e32 v2, 16, v2
	v_and_or_b32 v0, v1, s29, v0
	v_and_or_b32 v1, v3, s29, v2
	global_store_dwordx2 v[18:19], v[0:1], off offset:512 sc1
	global_store_dwordx4 v[20:21], v[26:29], off offset:2048 sc1
	v_mul_f32_e32 v4, v26, v25
	v_mul_f32_e32 v6, v28, v25
	v_mul_f32_e32 v5, v27, v25
	v_mul_f32_e32 v7, v29, v25
	s_waitcnt vmcnt(6)
	v_mul_f32_e32 v0, v4, v122
	v_mul_f32_e32 v2, v6, v124
	v_mul_f32_e32 v1, v5, v123
	v_mul_f32_e32 v3, v7, v125
	v_bfe_u32 v4, v0, 16, 1
	v_bfe_u32 v6, v2, 16, 1
	v_bfe_u32 v5, v1, 16, 1
	v_bfe_u32 v7, v3, 16, 1
	v_add3_u32 v0, v0, v4, s28
	v_add3_u32 v2, v2, v6, s28
	v_add3_u32 v1, v1, v5, s28
	v_add3_u32 v3, v3, v7, s28
	v_lshrrev_b32_e32 v0, 16, v0
	v_lshrrev_b32_e32 v2, 16, v2
	v_and_or_b32 v0, v1, s29, v0
	v_and_or_b32 v1, v3, s29, v2
	global_store_dwordx2 v[18:19], v[0:1], off offset:1024 sc1
	global_store_dwordx4 v[20:21], v[30:33], off offset:3072 sc1
	v_mul_f32_e32 v4, v30, v25
	v_mul_f32_e32 v6, v32, v25
	v_mul_f32_e32 v5, v31, v25
	v_mul_f32_e32 v7, v33, v25
	s_waitcnt vmcnt(7)
	v_mul_f32_e32 v0, v4, v126
	v_mul_f32_e32 v2, v6, v128
	v_mul_f32_e32 v1, v5, v127
	v_mul_f32_e32 v3, v7, v129
	v_bfe_u32 v4, v0, 16, 1
	v_bfe_u32 v6, v2, 16, 1
	v_bfe_u32 v5, v1, 16, 1
	v_bfe_u32 v7, v3, 16, 1
	v_add3_u32 v0, v0, v4, s28
	v_add3_u32 v2, v2, v6, s28
	v_add3_u32 v1, v1, v5, s28
	v_add3_u32 v3, v3, v7, s28
	v_lshrrev_b32_e32 v0, 16, v0
	v_lshrrev_b32_e32 v2, 16, v2
	v_and_or_b32 v0, v1, s29, v0
	v_and_or_b32 v1, v3, s29, v2
	global_store_dwordx2 v[18:19], v[0:1], off offset:1536 sc1
	s_cbranch_scc0 .LBB0_832

.LBB0_1062:
	v_lshl_add_u64 v[70:71], s[10:11], 0, v[6:7]
	v_add_co_u32_e32 v46, vcc, 0x29900000, v70
	v_lshl_add_u64 v[8:9], s[10:11], 0, v[4:5]
	s_nop 0
	v_addc_co_u32_e32 v47, vcc, 0, v71, vcc
	v_add_co_u32_e64 v86, s[4:5], s1, v8
	v_add_co_u32_e32 v54, vcc, 0x29980000, v70
	s_nop 0
	v_addc_co_u32_e64 v87, s[4:5], 0, v9, s[4:5]
	v_addc_co_u32_e32 v55, vcc, 0, v71, vcc
	global_load_dwordx4 v[14:17], v[0:1], off
	global_load_dwordx4 v[18:21], v[86:87], off
	v_add_co_u32_e32 v72, vcc, 0x29a00000, v70
	global_load_dwordx4 v[22:25], v[46:47], off
	global_load_dwordx4 v[26:29], v[46:47], off offset:1024
	global_load_dwordx4 v[30:33], v[46:47], off offset:2048
	global_load_dwordx4 v[34:37], v[46:47], off offset:3072
	global_load_dwordx4 v[38:41], v[54:55], off
	global_load_dwordx4 v[42:45], v[54:55], off offset:1024
	v_addc_co_u32_e32 v73, vcc, 0, v71, vcc
	global_load_dwordx4 v[46:49], v[54:55], off offset:2048
	global_load_dwordx4 v[50:53], v[54:55], off offset:3072
	v_add_co_u32_e32 v88, vcc, 0x29a80000, v70
	global_load_dwordx4 v[54:57], v[72:73], off
	global_load_dwordx4 v[58:61], v[72:73], off offset:1024
	global_load_dwordx4 v[62:65], v[72:73], off offset:2048
	global_load_dwordx4 v[66:69], v[72:73], off offset:3072
	v_addc_co_u32_e32 v89, vcc, 0, v71, vcc
	global_load_dwordx4 v[70:73], v[88:89], off
	global_load_dwordx4 v[74:77], v[88:89], off offset:1024
	global_load_dwordx4 v[78:81], v[88:89], off offset:2048
	global_load_dwordx4 v[82:85], v[88:89], off offset:3072
	global_load_dwordx4 v[90:93], v[86:87], off offset:1024
	global_load_dwordx4 v[94:97], v[0:1], off offset:1024
	global_load_dwordx4 v[98:101], v[86:87], off offset:2048
	global_load_dwordx4 v[102:105], v[0:1], off offset:2048
	global_load_dwordx4 v[106:109], v[86:87], off offset:3072
	global_load_dwordx4 v[110:113], v[0:1], off offset:3072
	v_add_co_u32_e64 v8, s[4:5], s15, v8
	v_lshl_add_u64 v[10:11], s[10:11], 0, v[2:3]
	s_nop 0
	v_addc_co_u32_e64 v9, s[4:5], 0, v9, s[4:5]
	v_add_co_u32_e64 v10, s[4:5], s26, v10
	s_add_i32 s16, s16, s18
	s_nop 0
	v_addc_co_u32_e64 v11, s[4:5], 0, v11, s[4:5]
	v_lshl_add_u64 v[2:3], v[2:3], 0, s[22:23]
	v_lshl_add_u64 v[4:5], v[4:5], 0, s[24:25]
	v_lshl_add_u64 v[6:7], v[6:7], 0, s[24:25]
	s_cmpk_gt_i32 s16, 0x407f
	s_waitcnt vmcnt(17)
	v_pk_add_f32 v[24:25], v[24:25], v[40:41]
	v_pk_add_f32 v[22:23], v[22:23], v[38:39]
	s_waitcnt vmcnt(16)
	v_pk_add_f32 v[28:29], v[28:29], v[44:45]
	v_pk_add_f32 v[26:27], v[26:27], v[42:43]
	s_waitcnt vmcnt(15)
	v_pk_add_f32 v[32:33], v[32:33], v[48:49]
	v_pk_add_f32 v[30:31], v[30:31], v[46:47]
	s_waitcnt vmcnt(13)
	v_pk_add_f32 v[24:25], v[24:25], v[56:57]
	v_pk_add_f32 v[22:23], v[22:23], v[54:55]
	s_waitcnt vmcnt(12)
	v_pk_add_f32 v[28:29], v[28:29], v[60:61]
	v_pk_add_f32 v[26:27], v[26:27], v[58:59]
	v_pk_add_f32 v[36:37], v[36:37], v[52:53]
	v_pk_add_f32 v[34:35], v[34:35], v[50:51]
	s_waitcnt vmcnt(11)
	v_pk_add_f32 v[32:33], v[32:33], v[64:65]
	v_pk_add_f32 v[30:31], v[30:31], v[62:63]
	s_waitcnt vmcnt(9)
	v_pk_add_f32 v[24:25], v[24:25], v[72:73]
	v_pk_add_f32 v[22:23], v[22:23], v[70:71]
	s_waitcnt vmcnt(8)
	v_pk_add_f32 v[28:29], v[28:29], v[76:77]
	v_pk_add_f32 v[26:27], v[26:27], v[74:75]
	v_pk_add_f32 v[36:37], v[36:37], v[68:69]
	v_pk_add_f32 v[34:35], v[34:35], v[66:67]
	s_waitcnt vmcnt(7)
	v_pk_add_f32 v[32:33], v[32:33], v[80:81]
	v_pk_add_f32 v[30:31], v[30:31], v[78:79]
	v_mul_f32_e32 v38, v23, v23
	v_mul_f32_e32 v39, v25, v25
	v_mul_f32_e32 v40, v27, v27
	v_mul_f32_e32 v41, v29, v29
	s_waitcnt vmcnt(6)
	v_pk_add_f32 v[36:37], v[36:37], v[84:85]
	v_pk_add_f32 v[34:35], v[34:35], v[82:83]
	v_mul_f32_e32 v42, v31, v31
	v_mul_f32_e32 v43, v33, v33
	v_fmac_f32_e32 v38, v22, v22
	v_fmac_f32_e32 v39, v24, v24
	v_fmac_f32_e32 v40, v26, v26
	v_fmac_f32_e32 v41, v28, v28
	v_mul_f32_e32 v44, v35, v35
	v_mul_f32_e32 v45, v37, v37
	v_fmac_f32_e32 v42, v30, v30
	v_fmac_f32_e32 v43, v32, v32
	v_add_f32_e32 v38, v38, v39
	v_add_f32_e32 v39, v40, v41
	v_fmac_f32_e32 v44, v34, v34
	v_fmac_f32_e32 v45, v36, v36
	v_add_f32_e32 v40, v42, v43
	v_add_f32_e32 v38, v38, v39
	v_add_f32_e32 v41, v44, v45
	v_add_f32_e32 v38, v38, v40
	v_add_f32_e32 v38, v38, v41
	s_nop 1
	v_add_f32_dpp v38, v38, v38 quad_perm:[1,0,3,2] row_mask:0xf bank_mask:0xf bound_ctrl:1
	s_nop 1
	v_add_f32_dpp v38, v38, v38 quad_perm:[2,3,0,1] row_mask:0xf bank_mask:0xf bound_ctrl:1
	s_nop 1
	v_add_f32_dpp v38, v38, v38 row_half_mirror row_mask:0xf bank_mask:0xf bound_ctrl:1
	s_nop 1
	v_add_f32_dpp v38, v38, v38 row_ror:8 row_mask:0xf bank_mask:0xf bound_ctrl:1
	v_mov_b32_e32 v39, v38
	s_nop 1
	v_permlane16_swap_b32_e32 v38, v39
	v_add_f32_e32 v38, v38, v39
	v_mov_b32_e32 v39, v38
	s_nop 1
	v_permlane32_swap_b32_e32 v38, v39
	v_add_f32_e32 v38, v38, v39
	v_fmamk_f32 v38, v38, 0x3a800000, v12
	v_mul_f32_e32 v39, 0x4f800000, v38
	v_cmp_gt_f32_e32 vcc, s0, v38
	s_nop 1
	v_cndmask_b32_e32 v38, v38, v39, vcc
	v_sqrt_f32_e32 v39, v38
	s_nop 0
	v_add_u32_e32 v40, -1, v39
	v_add_u32_e32 v41, 1, v39
	v_fma_f32 v42, -v40, v39, v38
	v_fma_f32 v43, -v41, v39, v38
	v_cmp_ge_f32_e64 s[4:5], 0, v42
	s_nop 1
	v_cndmask_b32_e64 v39, v39, v40, s[4:5]
	v_cmp_lt_f32_e64 s[4:5], 0, v43
	s_nop 1
	v_cndmask_b32_e64 v39, v39, v41, s[4:5]
	v_mul_f32_e32 v40, 0x37800000, v39
	v_cndmask_b32_e32 v39, v39, v40, vcc
	v_cmp_class_f32_e32 vcc, v38, v13
	s_nop 1
	v_cndmask_b32_e32 v38, v39, v38, vcc
	v_div_scale_f32 v39, s[4:5], v38, v38, 1.0
	v_rcp_f32_e32 v41, v39
	v_div_scale_f32 v40, vcc, 1.0, v38, 1.0
	v_fma_f32 v42, -v39, v41, 1.0
	v_fmac_f32_e32 v41, v42, v41
	v_mul_f32_e32 v42, v40, v41
	v_fma_f32 v43, -v39, v42, v40
	v_fmac_f32_e32 v42, v43, v41
	v_fma_f32 v39, -v39, v42, v40
	v_div_fmas_f32 v39, v39, v41, v42
	v_div_fixup_f32 v38, v39, v38, 1.0
	v_pk_mul_f32 v[22:23], v[22:23], v[38:39] op_sel_hi:[1,0]
	v_pk_mul_f32 v[24:25], v[24:25], v[38:39] op_sel_hi:[1,0]
	v_pk_fma_f32 v[14:15], v[14:15], v[22:23], v[18:19]
	v_pk_fma_f32 v[16:17], v[16:17], v[24:25], v[20:21]
	v_bfe_u32 v18, v14, 16, 1
	v_bfe_u32 v20, v16, 16, 1
	global_store_dwordx4 v[8:9], v[14:17], off sc1
	v_bfe_u32 v19, v15, 16, 1
	v_bfe_u32 v21, v17, 16, 1
	v_add3_u32 v14, v14, v18, s17
	v_add3_u32 v16, v16, v20, s17
	v_add3_u32 v15, v15, v19, s17
	v_add3_u32 v17, v17, v21, s17
	v_lshrrev_b32_e32 v14, 16, v14
	v_lshrrev_b32_e32 v16, 16, v16
	v_and_or_b32 v14, v15, s19, v14
	v_and_or_b32 v15, v17, s19, v16
	global_store_dwordx2 v[10:11], v[14:15], off sc1
	s_nop 0
	v_pk_mul_f32 v[22:23], v[28:29], v[38:39] op_sel_hi:[1,0]
	v_pk_mul_f32 v[24:25], v[26:27], v[38:39] op_sel_hi:[1,0]
	s_waitcnt vmcnt(6)
	v_pk_fma_f32 v[16:17], v[96:97], v[22:23], v[92:93]
	v_pk_fma_f32 v[14:15], v[94:95], v[24:25], v[90:91]
	v_bfe_u32 v20, v16, 16, 1
	v_bfe_u32 v18, v14, 16, 1
	global_store_dwordx4 v[8:9], v[14:17], off offset:1024 sc1
	v_bfe_u32 v19, v15, 16, 1
	v_bfe_u32 v21, v17, 16, 1
	v_add3_u32 v14, v14, v18, s17
	v_add3_u32 v16, v16, v20, s17
	v_add3_u32 v15, v15, v19, s17
	v_add3_u32 v17, v17, v21, s17
	v_lshrrev_b32_e32 v14, 16, v14
	v_lshrrev_b32_e32 v16, 16, v16
	v_and_or_b32 v14, v15, s19, v14
	v_and_or_b32 v15, v17, s19, v16
	global_store_dwordx2 v[10:11], v[14:15], off offset:512 sc1
	s_nop 0
	v_pk_mul_f32 v[22:23], v[32:33], v[38:39] op_sel_hi:[1,0]
	v_pk_mul_f32 v[24:25], v[30:31], v[38:39] op_sel_hi:[1,0]
	s_waitcnt vmcnt(6)
	v_pk_fma_f32 v[16:17], v[22:23], v[104:105], v[100:101]
	v_pk_fma_f32 v[14:15], v[24:25], v[102:103], v[98:99]
	v_bfe_u32 v20, v16, 16, 1
	v_bfe_u32 v18, v14, 16, 1
	global_store_dwordx4 v[8:9], v[14:17], off offset:2048 sc1
	v_bfe_u32 v19, v15, 16, 1
	v_bfe_u32 v21, v17, 16, 1
	v_add3_u32 v14, v14, v18, s17
	v_add3_u32 v16, v16, v20, s17
	v_add3_u32 v15, v15, v19, s17
	v_add3_u32 v17, v17, v21, s17
	v_lshrrev_b32_e32 v14, 16, v14
	v_lshrrev_b32_e32 v16, 16, v16
	v_and_or_b32 v14, v15, s19, v14
	v_and_or_b32 v15, v17, s19, v16
	global_store_dwordx2 v[10:11], v[14:15], off offset:1024 sc1
	s_nop 0
	v_pk_mul_f32 v[22:23], v[36:37], v[38:39] op_sel_hi:[1,0]
	v_pk_mul_f32 v[24:25], v[34:35], v[38:39] op_sel_hi:[1,0]
	s_waitcnt vmcnt(6)
	v_pk_fma_f32 v[16:17], v[22:23], v[112:113], v[108:109]
	v_pk_fma_f32 v[14:15], v[24:25], v[110:111], v[106:107]
	global_store_dwordx4 v[8:9], v[14:17], off offset:3072 sc1
	v_bfe_u32 v8, v14, 16, 1
	v_bfe_u32 v18, v16, 16, 1
	v_bfe_u32 v9, v15, 16, 1
	v_bfe_u32 v19, v17, 16, 1
	v_add3_u32 v8, v14, v8, s17
	v_add3_u32 v14, v16, v18, s17
	v_add3_u32 v9, v15, v9, s17
	v_add3_u32 v15, v17, v19, s17
	v_lshrrev_b32_e32 v8, 16, v8
	v_lshrrev_b32_e32 v14, 16, v14
	v_and_or_b32 v8, v9, s19, v8
	v_and_or_b32 v9, v15, s19, v14
	global_store_dwordx2 v[10:11], v[8:9], off offset:1536 sc1
	s_cbranch_scc0 .LBB0_1062
